# prologue init_rows: the row's 8 f32 loads issued together with negative immediates and counted vmcnt waits per 16B-pair chunk instead of four load-wait round trips
# speedup vs baseline: 1.0067x; 1.0005x over previous
; __device__ __forceinline__ void unpack8(const u32x4 w, float (&f)[8]) { f[0] = bflo(w.x); f[1] = bfhi(w.x); f[2] = bflo(w.y); f[3] = bfhi(w.y); f[4] = bflo(w.z); f[5] = bfhi(w.z); f[6] = bflo(w.w); f[7] = bfhi(w.w); }
; __device__ __forceinline__ u32x4 pack8(const float (&f)[8]) { u32x4 w; w.x = pk_bf16(f[0], f[1]); w.y = pk_bf16(f[2], f[3]); w.z = pk_bf16(f[4], f[5]); w.w = pk_bf16(f[6], f[7]); return w; }
; __device__ __forceinline__ void init_rows(const float* x32, bf16* h16, float* ssp, int gw, int ngw, int lane) {
;     for (int m = gw; m < T; m += ngw) { float s = 0.f;
; #pragma unroll
;         for (int j = 0; j < 4; ++j) { float v[8]; ld8f(x32 + (size_t)m * D + (64 * j + lane) * 8, v); const u32x4 w = pack8(v); *(u32x4*)(h16 + (size_t)m * D + (64 * j + lane) * 8) = w; unpack8(w, v);
; #pragma unroll
;             for (int e = 0; e < 8; ++e) s += v[e] * v[e]; }
;         s = wave_sum(s);
;         if (lane < 32) ssp[(size_t)m * 32 + lane] = (lane == 0) ? s : 0.f; }
; }
.LBB0_131:
	s_waitcnt lgkmcnt(0)
	global_load_dwordx4 v[36:39], v[4:5], off offset:-4096
	global_load_dwordx4 v[40:43], v[4:5], off offset:-4080
	global_load_dwordx4 v[44:47], v[4:5], off offset:-2048
	global_load_dwordx4 v[48:51], v[4:5], off offset:-2032
	global_load_dwordx4 v[52:55], v[4:5], off
	global_load_dwordx4 v[56:59], v[4:5], off offset:16
	global_load_dwordx4 v[60:63], v[4:5], off offset:2048
	global_load_dwordx4 v[64:67], v[4:5], off offset:2064
	v_lshl_add_u64 v[20:21], s[88:89], 0, v[2:3]
	v_add_co_u32_e32 v32, vcc, s47, v20
	s_nop 1
	v_addc_co_u32_e32 v33, vcc, 0, v21, vcc
	s_waitcnt vmcnt(6)
	v_cvt_pk_bf16_f32 v16, v36, v37
	v_cvt_pk_bf16_f32 v17, v38, v39
	v_cvt_pk_bf16_f32 v18, v40, v41
	v_cvt_pk_bf16_f32 v19, v42, v43
	global_store_dwordx4 v[32:33], v[16:19], off
	v_lshlrev_b32_e32 v34, 16, v16
	v_and_b32_e32 v12, 0xffff0000, v16
	v_mul_f32_e32 v12, v12, v12
	v_fmac_f32_e32 v12, v34, v34
	v_lshlrev_b32_e32 v13, 16, v17
	v_fmac_f32_e32 v12, v13, v13
	v_and_b32_e32 v14, 0xffff0000, v17
	v_fmac_f32_e32 v12, v14, v14
	v_lshlrev_b32_e32 v15, 16, v18
	v_fmac_f32_e32 v12, v15, v15
	v_and_b32_e32 v13, 0xffff0000, v18
	v_fmac_f32_e32 v12, v13, v13
	v_lshlrev_b32_e32 v14, 16, v19
	v_fmac_f32_e32 v12, v14, v14
	v_and_b32_e32 v15, 0xffff0000, v19
	v_fmac_f32_e32 v12, v15, v15
	s_waitcnt vmcnt(5)
	v_cvt_pk_bf16_f32 v20, v44, v45
	v_cvt_pk_bf16_f32 v21, v46, v47
	v_cvt_pk_bf16_f32 v22, v48, v49
	v_cvt_pk_bf16_f32 v23, v50, v51
	global_store_dwordx4 v[32:33], v[20:23], off offset:1024
	v_lshlrev_b32_e32 v13, 16, v20
	v_fmac_f32_e32 v12, v13, v13
	v_and_b32_e32 v14, 0xffff0000, v20
	v_fmac_f32_e32 v12, v14, v14
	v_lshlrev_b32_e32 v15, 16, v21
	v_fmac_f32_e32 v12, v15, v15
	v_and_b32_e32 v13, 0xffff0000, v21
	v_fmac_f32_e32 v12, v13, v13
	v_lshlrev_b32_e32 v14, 16, v22
	v_fmac_f32_e32 v12, v14, v14
	v_and_b32_e32 v15, 0xffff0000, v22
	v_fmac_f32_e32 v12, v15, v15
	v_lshlrev_b32_e32 v13, 16, v23
	v_fmac_f32_e32 v12, v13, v13
	v_and_b32_e32 v14, 0xffff0000, v23
	v_fmac_f32_e32 v12, v14, v14
	s_waitcnt vmcnt(4)
	v_cvt_pk_bf16_f32 v24, v52, v53
	v_cvt_pk_bf16_f32 v25, v54, v55
	v_cvt_pk_bf16_f32 v26, v56, v57
	v_cvt_pk_bf16_f32 v27, v58, v59
	global_store_dwordx4 v[32:33], v[24:27], off offset:2048
	v_lshlrev_b32_e32 v13, 16, v24
	v_fmac_f32_e32 v12, v13, v13
	v_and_b32_e32 v14, 0xffff0000, v24
	v_fmac_f32_e32 v12, v14, v14
	v_lshlrev_b32_e32 v15, 16, v25
	v_fmac_f32_e32 v12, v15, v15
	v_and_b32_e32 v13, 0xffff0000, v25
	v_fmac_f32_e32 v12, v13, v13
	v_lshlrev_b32_e32 v14, 16, v26
	v_fmac_f32_e32 v12, v14, v14
	v_and_b32_e32 v15, 0xffff0000, v26
	v_fmac_f32_e32 v12, v15, v15
	v_lshlrev_b32_e32 v13, 16, v27
	v_fmac_f32_e32 v12, v13, v13
	v_and_b32_e32 v14, 0xffff0000, v27
	v_fmac_f32_e32 v12, v14, v14
	s_waitcnt vmcnt(3)
	v_cvt_pk_bf16_f32 v28, v60, v61
	v_cvt_pk_bf16_f32 v29, v62, v63
	v_cvt_pk_bf16_f32 v30, v64, v65
	v_cvt_pk_bf16_f32 v31, v66, v67
	global_store_dwordx4 v[32:33], v[28:31], off offset:3072
	v_lshlrev_b32_e32 v13, 16, v28
	v_fmac_f32_e32 v12, v13, v13
	v_and_b32_e32 v14, 0xffff0000, v28
	v_fmac_f32_e32 v12, v14, v14
	v_lshlrev_b32_e32 v15, 16, v29
	v_fmac_f32_e32 v12, v15, v15
	v_and_b32_e32 v13, 0xffff0000, v29
	v_fmac_f32_e32 v12, v13, v13
	v_lshlrev_b32_e32 v14, 16, v30
	v_fmac_f32_e32 v12, v14, v14
	v_and_b32_e32 v15, 0xffff0000, v30
	v_fmac_f32_e32 v12, v15, v15
	v_lshlrev_b32_e32 v13, 16, v31
	v_fmac_f32_e32 v12, v13, v13
	v_and_b32_e32 v14, 0xffff0000, v31
	v_fmac_f32_e32 v12, v14, v14
	ds_bpermute_b32 v13, v6, v12
	s_waitcnt lgkmcnt(0)
	v_add_f32_e32 v12, v12, v13
	ds_bpermute_b32 v13, v7, v12
	s_waitcnt lgkmcnt(0)
	v_add_f32_e32 v12, v12, v13
	ds_bpermute_b32 v13, v8, v12
	s_waitcnt lgkmcnt(0)
	v_add_f32_e32 v12, v12, v13
	ds_bpermute_b32 v13, v9, v12
	s_waitcnt lgkmcnt(0)
	v_add_f32_e32 v12, v12, v13
	ds_bpermute_b32 v13, v10, v12
	s_waitcnt lgkmcnt(0)
	v_add_f32_e32 v12, v12, v13
	ds_bpermute_b32 v13, v11, v12
	s_and_saveexec_b64 s[0:1], s[38:39]
	s_cbranch_execz .LBB0_130
	s_waitcnt lgkmcnt(0)
	v_add_f32_e32 v12, v12, v13
	v_cndmask_b32_e64 v14, 0, v12, s[40:41]
	v_lshl_add_u64 v[12:13], s[88:89], 0, v[0:1]
	global_store_dword v[12:13], v14, off
	s_branch .LBB0_130
